# G1 K-loop DMA staging 3/5/3/5 variant (one Bs[.][1] piece moved), vmcnt 8/7/8/7
# speedup vs baseline: 1.0042x; 1.0032x over previous
.LBB0_110:
	v_lshrrev_b32_e32 v18, 1, v8
	v_and_b32_e32 v18, 24, v18
	v_and_b32_e32 v9, 15, v8
	v_lshlrev_b32_e32 v19, 1, v18
	v_lshlrev_b32_e32 v8, 2, v8
	v_lshl_or_b32 v142, s38, 6, v9
	v_lshl_or_b32 v9, v9, 6, v19
	s_lshl_b32 s8, s38, 13
	v_and_b32_e32 v8, 32, v8
	v_bitop3_b32 v19, v9, s8, v8 bitop3:0xde
	s_lshl_b32 s8, s25, 5
	s_and_b32 s10, s8, 0x60
	v_lshl_add_u64 v[10:11], s[56:57], 0, v[0:1]
	v_mov_b32_e32 v131, v1
	v_readlane_b32 s50, v254, 48
	s_lshl_b32 s8, s10, 7
	v_lshl_add_u64 v[12:13], s[56:57], 0, v[130:131]
	v_mov_b32_e32 v135, v1
	v_readlane_b32 s51, v254, 49
	v_bitop3_b32 v143, v9, s8, v8 bitop3:0xde
	s_add_i32 m0, s53, 0x18000
	v_lshl_add_u64 v[8:9], v[10:11], 0, s[26:27]
	v_lshl_add_u64 v[14:15], s[50:51], 0, v[134:135]
	v_mov_b32_e32 v133, v1
	s_waitcnt vmcnt(2)
	s_barrier
	global_load_lds_dwordx4 v[8:9], off
	v_lshl_add_u64 v[8:9], v[12:13], 0, s[26:27]
	s_add_i32 m0, s53, 0x1a000
	s_add_i32 s61, s53, 0x8000
	s_add_i32 s62, s53, 0xa000
	v_lshl_add_u64 v[16:17], s[50:51], 0, v[132:133]
	global_load_lds_dwordx4 v[8:9], off
	v_lshl_add_u64 v[8:9], v[14:15], 0, s[26:27]
	s_mov_b32 m0, s61
	s_add_u32 s8, s56, 0x40080
	global_load_lds_dwordx4 v[8:9], off
	v_lshl_add_u64 v[8:9], v[16:17], 0, s[26:27]
	s_mov_b32 m0, s62
	s_addc_u32 s9, s57, 0
	s_mov_b64 s[100:101], s[8:9]
	global_load_lds_dwordx4 v[8:9], off
	v_lshl_add_u64 v[8:9], s[8:9], 0, v[130:131]
	s_add_i32 m0, s53, 0x1e000
	s_cmpk_lt_u32 s24, 0x100
	global_load_lds_dwordx4 v[8:9], off
	v_lshlrev_b32_e32 v8, 14, v6
	v_and_b32_e32 v8, 0xffff8000, v8
	v_lshl_add_u32 v5, v5, 11, v8
	v_and_b32_e32 v6, 1, v6
	v_lshl_or_b32 v5, v6, 6, v5
	v_lshl_add_u32 v136, v7, 1, v5
	v_lshlrev_b32_e32 v5, 14, v2
	v_and_b32_e32 v5, 0xffff8000, v5
	s_waitcnt vmcnt(5)
	v_lshl_add_u32 v3, v3, 11, v5
	v_and_b32_e32 v2, 1, v2
	v_lshl_or_b32 v2, v2, 6, v3
	v_readlane_b32 s8, v254, 46
	s_cselect_b64 s[24:25], -1, 0
	v_or_b32_e32 v144, s10, v18
	v_mov_b32_e32 v137, v1
	v_lshl_add_u32 v138, v4, 1, v2
	v_mov_b32_e32 v139, v1
	s_mov_b32 s63, 0
	v_add_u32_e32 v145, 0, v19
	v_readlane_b32 s64, v254, 52
	s_mov_b32 s65, s8
	s_barrier
	v_readlane_b32 s9, v254, 47
	s_branch .LBB0_113

.LBB0_120:
	s_add_u32 s8, s50, 0xfffc0080
	s_addc_u32 s9, s51, -1
	s_add_i32 s10, 0, 0x10000
	s_cmp_eq_u32 s72, 12
	s_cselect_b32 s57, s43, s9
	s_cselect_b32 s56, s66, s8
	v_add_u32_e32 v140, s10, v143
	s_cselect_b32 s55, s41, s69
	s_cselect_b32 s54, s67, s68
	s_add_i32 s11, 0, 0x14000
	ds_read_b128 v[146:149], v140
	ds_read_b128 v[150:153], v140 offset:1024
	ds_read_b128 v[154:157], v140 offset:2048
	ds_read_b128 v[158:161], v140 offset:3072
	v_add_u32_e32 v140, s11, v143
	ds_read_b128 v[162:165], v140
	ds_read_b128 v[166:169], v140 offset:1024
	ds_read_b128 v[170:173], v140 offset:2048
	ds_read_b128 v[174:177], v140 offset:3072
	v_lshl_add_u64 v[140:141], s[100:101], 0, v[0:1]
	s_add_i32 m0, s52, 0x1c000
	s_nop 0
	global_load_lds_dwordx4 v[140:141], off
	v_lshl_add_u64 v[140:141], s[50:51], 0, v[136:137]
	s_add_i32 m0, s53, 0xc000
	ds_read_b128 v[178:181], v145
	ds_read_b128 v[182:185], v145 offset:1024
	ds_read_b128 v[224:227], v145 offset:2048
	ds_read_b128 v[228:231], v145 offset:3072
	ds_read_b128 v[232:235], v145 offset:4096
	ds_read_b128 v[236:239], v145 offset:5120
	ds_read_b128 v[240:243], v145 offset:6144
	ds_read_b128 v[244:247], v145 offset:7168
	global_load_lds_dwordx4 v[140:141], off
	v_lshl_add_u64 v[140:141], s[50:51], 0, v[138:139]
	s_add_i32 m0, s53, 0xe000
	s_nop 0
	global_load_lds_dwordx4 v[140:141], off
	s_waitcnt vmcnt(8)
	s_waitcnt lgkmcnt(0)
	s_barrier
	s_setprio 1
	s_waitcnt lgkmcnt(0)
	v_mfma_f32_16x16x32_bf16 v[126:129], v[146:149], v[178:181], v[126:129]
	v_mfma_f32_16x16x32_bf16 v[118:121], v[154:157], v[178:181], v[118:121]
	v_mfma_f32_16x16x32_bf16 v[110:113], v[146:149], v[224:227], v[110:113]
	v_mfma_f32_16x16x32_bf16 v[102:105], v[154:157], v[224:227], v[102:105]
	v_mfma_f32_16x16x32_bf16 v[94:97], v[146:149], v[232:235], v[94:97]
	v_mfma_f32_16x16x32_bf16 v[86:89], v[154:157], v[232:235], v[86:89]
	v_mfma_f32_16x16x32_bf16 v[78:81], v[146:149], v[240:243], v[78:81]
	v_mfma_f32_16x16x32_bf16 v[70:73], v[154:157], v[240:243], v[70:73]
	v_mfma_f32_16x16x32_bf16 v[126:129], v[150:153], v[182:185], v[126:129]
	v_mfma_f32_16x16x32_bf16 v[118:121], v[158:161], v[182:185], v[118:121]
	v_mfma_f32_16x16x32_bf16 v[110:113], v[150:153], v[228:231], v[110:113]
	v_mfma_f32_16x16x32_bf16 v[102:105], v[158:161], v[228:231], v[102:105]
	v_mfma_f32_16x16x32_bf16 v[94:97], v[150:153], v[236:239], v[94:97]
	v_mfma_f32_16x16x32_bf16 v[86:89], v[158:161], v[236:239], v[86:89]
	v_mfma_f32_16x16x32_bf16 v[78:81], v[150:153], v[244:247], v[78:81]
	v_mfma_f32_16x16x32_bf16 v[70:73], v[158:161], v[244:247], v[70:73]
	s_setprio 0
	s_setprio 1
	v_mfma_f32_16x16x32_bf16 v[122:125], v[162:165], v[178:181], v[122:125]
	v_mfma_f32_16x16x32_bf16 v[114:117], v[170:173], v[178:181], v[114:117]
	v_mfma_f32_16x16x32_bf16 v[106:109], v[162:165], v[224:227], v[106:109]
	v_mfma_f32_16x16x32_bf16 v[98:101], v[170:173], v[224:227], v[98:101]
	v_mfma_f32_16x16x32_bf16 v[90:93], v[162:165], v[232:235], v[90:93]
	v_mfma_f32_16x16x32_bf16 v[82:85], v[170:173], v[232:235], v[82:85]
	v_mfma_f32_16x16x32_bf16 v[74:77], v[162:165], v[240:243], v[74:77]
	v_mfma_f32_16x16x32_bf16 v[66:69], v[170:173], v[240:243], v[66:69]
	v_mfma_f32_16x16x32_bf16 v[122:125], v[166:169], v[182:185], v[122:125]
	v_mfma_f32_16x16x32_bf16 v[114:117], v[174:177], v[182:185], v[114:117]
	v_mfma_f32_16x16x32_bf16 v[106:109], v[166:169], v[228:231], v[106:109]
	v_mfma_f32_16x16x32_bf16 v[98:101], v[174:177], v[228:231], v[98:101]
	v_mfma_f32_16x16x32_bf16 v[90:93], v[166:169], v[236:239], v[90:93]
	v_mfma_f32_16x16x32_bf16 v[82:85], v[174:177], v[236:239], v[82:85]
	v_mfma_f32_16x16x32_bf16 v[74:77], v[166:169], v[244:247], v[74:77]
	v_mfma_f32_16x16x32_bf16 v[66:69], v[174:177], v[244:247], v[66:69]
	s_setprio 0
	s_barrier
	s_add_i32 s8, s10, s52
	v_lshl_add_u64 v[140:141], s[54:55], 0, v[0:1]
	s_mov_b32 m0, s8
	ds_read_b128 v[178:181], v145 offset:16384
	ds_read_b128 v[182:185], v145 offset:17408
	ds_read_b128 v[224:227], v145 offset:18432
	ds_read_b128 v[228:231], v145 offset:19456
	ds_read_b128 v[232:235], v145 offset:20480
	ds_read_b128 v[236:239], v145 offset:21504
	ds_read_b128 v[240:243], v145 offset:22528
	ds_read_b128 v[244:247], v145 offset:23552
	global_load_lds_dwordx4 v[140:141], off
	s_add_i32 m0, s8, 0x2000
	s_add_u32 s8, s54, 0x40000
	v_lshl_add_u64 v[186:187], s[54:55], 0, v[130:131]
	s_addc_u32 s9, s55, 0
	s_add_i32 s10, s11, s52
	global_load_lds_dwordx4 v[186:187], off
	v_lshl_add_u64 v[248:249], s[56:57], 0, v[132:133]
	v_lshl_add_u64 v[202:203], s[8:9], 0, v[130:131]
	s_add_i32 m0, s10, 0x2000
	s_nop 0
	global_load_lds_dwordx4 v[202:203], off
	v_lshl_add_u64 v[202:203], s[56:57], 0, v[134:135]
	s_mov_b32 m0, s53
	s_nop 0
	global_load_lds_dwordx4 v[202:203], off
	s_mov_b32 m0, s58
	s_nop 0
	global_load_lds_dwordx4 v[248:249], off
	s_waitcnt vmcnt(7)
	s_waitcnt lgkmcnt(0)
	s_barrier
	s_setprio 1
	s_waitcnt lgkmcnt(0)
	v_mfma_f32_16x16x32_bf16 v[62:65], v[146:149], v[178:181], v[62:65]
	v_mfma_f32_16x16x32_bf16 v[54:57], v[154:157], v[178:181], v[54:57]
	v_mfma_f32_16x16x32_bf16 v[46:49], v[146:149], v[224:227], v[46:49]
	v_mfma_f32_16x16x32_bf16 v[38:41], v[154:157], v[224:227], v[38:41]
	v_mfma_f32_16x16x32_bf16 v[30:33], v[146:149], v[232:235], v[30:33]
	v_mfma_f32_16x16x32_bf16 v[22:25], v[154:157], v[232:235], v[22:25]
	v_mfma_f32_16x16x32_bf16 v[14:17], v[146:149], v[240:243], v[14:17]
	v_mfma_f32_16x16x32_bf16 v[6:9], v[154:157], v[240:243], v[6:9]
	v_mfma_f32_16x16x32_bf16 v[62:65], v[150:153], v[182:185], v[62:65]
	v_mfma_f32_16x16x32_bf16 v[54:57], v[158:161], v[182:185], v[54:57]
	v_mfma_f32_16x16x32_bf16 v[46:49], v[150:153], v[228:231], v[46:49]
	v_mfma_f32_16x16x32_bf16 v[38:41], v[158:161], v[228:231], v[38:41]
	v_mfma_f32_16x16x32_bf16 v[30:33], v[150:153], v[236:239], v[30:33]
	v_mfma_f32_16x16x32_bf16 v[22:25], v[158:161], v[236:239], v[22:25]
	v_mfma_f32_16x16x32_bf16 v[14:17], v[150:153], v[244:247], v[14:17]
	v_mfma_f32_16x16x32_bf16 v[6:9], v[158:161], v[244:247], v[6:9]
	s_setprio 0
	s_setprio 1
	v_mfma_f32_16x16x32_bf16 v[58:61], v[162:165], v[178:181], v[58:61]
	v_mfma_f32_16x16x32_bf16 v[50:53], v[170:173], v[178:181], v[50:53]
	v_mfma_f32_16x16x32_bf16 v[42:45], v[162:165], v[224:227], v[42:45]
	v_mfma_f32_16x16x32_bf16 v[34:37], v[170:173], v[224:227], v[34:37]
	v_mfma_f32_16x16x32_bf16 v[26:29], v[162:165], v[232:235], v[26:29]
	v_mfma_f32_16x16x32_bf16 v[18:21], v[170:173], v[232:235], v[18:21]
	v_mfma_f32_16x16x32_bf16 v[10:13], v[162:165], v[240:243], v[10:13]
	v_mfma_f32_16x16x32_bf16 v[2:5], v[170:173], v[240:243], v[2:5]
	v_mfma_f32_16x16x32_bf16 v[58:61], v[166:169], v[182:185], v[58:61]
	v_mfma_f32_16x16x32_bf16 v[50:53], v[174:177], v[182:185], v[50:53]
	v_mfma_f32_16x16x32_bf16 v[42:45], v[166:169], v[228:231], v[42:45]
	v_mfma_f32_16x16x32_bf16 v[34:37], v[174:177], v[228:231], v[34:37]
	v_mfma_f32_16x16x32_bf16 v[26:29], v[166:169], v[236:239], v[26:29]
	v_mfma_f32_16x16x32_bf16 v[18:21], v[174:177], v[236:239], v[18:21]
	v_mfma_f32_16x16x32_bf16 v[10:13], v[166:169], v[244:247], v[10:13]
	v_mfma_f32_16x16x32_bf16 v[2:5], v[174:177], v[244:247], v[2:5]
	s_setprio 0
	s_barrier
	s_add_i32 s10, 0, 0x18000
	s_add_i32 s11, 0, 0x1c000
	v_add_u32_e32 v158, s10, v143
	v_add_u32_e32 v174, s11, v143
	ds_read_b128 v[146:149], v158
	ds_read_b128 v[150:153], v158 offset:1024
	ds_read_b128 v[154:157], v158 offset:2048
	ds_read_b128 v[158:161], v158 offset:3072
	ds_read_b128 v[162:165], v174
	ds_read_b128 v[166:169], v174 offset:1024
	ds_read_b128 v[170:173], v174 offset:2048
	ds_read_b128 v[174:177], v174 offset:3072
	s_add_u32 s100, s54, 0x40000
	s_addc_u32 s101, s55, 0
	v_lshl_add_u64 v[250:251], s[100:101], 0, v[0:1]
	s_add_i32 m0, s52, 0x14000
	s_nop 0
	global_load_lds_dwordx4 v[250:251], off
	s_add_u32 s8, s56, 0x40000
	s_addc_u32 s9, s57, 0
	s_mov_b32 m0, s59
	v_lshl_add_u64 v[250:251], s[8:9], 0, v[134:135]
	ds_read_b128 v[178:181], v145 offset:32768
	ds_read_b128 v[182:185], v145 offset:33792
	ds_read_b128 v[224:227], v145 offset:34816
	ds_read_b128 v[228:231], v145 offset:35840
	ds_read_b128 v[232:235], v145 offset:36864
	ds_read_b128 v[236:239], v145 offset:37888
	ds_read_b128 v[240:243], v145 offset:38912
	ds_read_b128 v[244:247], v145 offset:39936
	global_load_lds_dwordx4 v[250:251], off
	v_lshl_add_u64 v[250:251], s[8:9], 0, v[132:133]
	s_mov_b32 m0, s60
	s_nop 0
	global_load_lds_dwordx4 v[250:251], off
	s_waitcnt vmcnt(8)
	s_waitcnt lgkmcnt(0)
	s_barrier
	s_setprio 1
	s_waitcnt lgkmcnt(0)
	v_mfma_f32_16x16x32_bf16 v[126:129], v[146:149], v[178:181], v[126:129]
	v_mfma_f32_16x16x32_bf16 v[118:121], v[154:157], v[178:181], v[118:121]
	v_mfma_f32_16x16x32_bf16 v[110:113], v[146:149], v[224:227], v[110:113]
	v_mfma_f32_16x16x32_bf16 v[102:105], v[154:157], v[224:227], v[102:105]
	v_mfma_f32_16x16x32_bf16 v[94:97], v[146:149], v[232:235], v[94:97]
	v_mfma_f32_16x16x32_bf16 v[86:89], v[154:157], v[232:235], v[86:89]
	v_mfma_f32_16x16x32_bf16 v[78:81], v[146:149], v[240:243], v[78:81]
	v_mfma_f32_16x16x32_bf16 v[70:73], v[154:157], v[240:243], v[70:73]
	v_mfma_f32_16x16x32_bf16 v[126:129], v[150:153], v[182:185], v[126:129]
	v_mfma_f32_16x16x32_bf16 v[118:121], v[158:161], v[182:185], v[118:121]
	v_mfma_f32_16x16x32_bf16 v[110:113], v[150:153], v[228:231], v[110:113]
	v_mfma_f32_16x16x32_bf16 v[102:105], v[158:161], v[228:231], v[102:105]
	v_mfma_f32_16x16x32_bf16 v[94:97], v[150:153], v[236:239], v[94:97]
	v_mfma_f32_16x16x32_bf16 v[86:89], v[158:161], v[236:239], v[86:89]
	v_mfma_f32_16x16x32_bf16 v[78:81], v[150:153], v[244:247], v[78:81]
	v_mfma_f32_16x16x32_bf16 v[70:73], v[158:161], v[244:247], v[70:73]
	s_setprio 0
	s_setprio 1
	v_mfma_f32_16x16x32_bf16 v[122:125], v[162:165], v[178:181], v[122:125]
	v_mfma_f32_16x16x32_bf16 v[114:117], v[170:173], v[178:181], v[114:117]
	v_mfma_f32_16x16x32_bf16 v[106:109], v[162:165], v[224:227], v[106:109]
	v_mfma_f32_16x16x32_bf16 v[98:101], v[170:173], v[224:227], v[98:101]
	v_mfma_f32_16x16x32_bf16 v[90:93], v[162:165], v[232:235], v[90:93]
	v_mfma_f32_16x16x32_bf16 v[82:85], v[170:173], v[232:235], v[82:85]
	v_mfma_f32_16x16x32_bf16 v[74:77], v[162:165], v[240:243], v[74:77]
	v_mfma_f32_16x16x32_bf16 v[66:69], v[170:173], v[240:243], v[66:69]
	v_mfma_f32_16x16x32_bf16 v[122:125], v[166:169], v[182:185], v[122:125]
	v_mfma_f32_16x16x32_bf16 v[114:117], v[174:177], v[182:185], v[114:117]
	v_mfma_f32_16x16x32_bf16 v[106:109], v[166:169], v[228:231], v[106:109]
	v_mfma_f32_16x16x32_bf16 v[98:101], v[174:177], v[228:231], v[98:101]
	v_mfma_f32_16x16x32_bf16 v[90:93], v[166:169], v[236:239], v[90:93]
	v_mfma_f32_16x16x32_bf16 v[82:85], v[174:177], v[236:239], v[82:85]
	v_mfma_f32_16x16x32_bf16 v[74:77], v[166:169], v[244:247], v[74:77]
	v_mfma_f32_16x16x32_bf16 v[66:69], v[174:177], v[244:247], v[66:69]
	s_setprio 0
	s_barrier
	s_add_i32 s8, s10, s52
	v_lshl_add_u64 v[140:141], v[140:141], 0, s[26:27]
	s_mov_b32 m0, s8
	ds_read_b128 v[178:181], v145 offset:49152
	ds_read_b128 v[182:185], v145 offset:50176
	ds_read_b128 v[224:227], v145 offset:51200
	ds_read_b128 v[228:231], v145 offset:52224
	ds_read_b128 v[232:235], v145 offset:53248
	ds_read_b128 v[236:239], v145 offset:54272
	ds_read_b128 v[240:243], v145 offset:55296
	ds_read_b128 v[244:247], v145 offset:56320
	global_load_lds_dwordx4 v[140:141], off
	s_add_i32 m0, s8, 0x2000
	s_add_u32 s8, s54, 0x40080
	v_lshl_add_u64 v[140:141], v[186:187], 0, s[26:27]
	s_addc_u32 s9, s55, 0
	s_mov_b64 s[100:101], s[8:9]
	s_add_i32 s10, s11, s52
	global_load_lds_dwordx4 v[140:141], off
	v_lshl_add_u64 v[140:141], s[8:9], 0, v[130:131]
	s_add_i32 m0, s10, 0x2000
	s_nop 0
	global_load_lds_dwordx4 v[140:141], off
	v_lshl_add_u64 v[140:141], v[202:203], 0, s[26:27]
	s_mov_b32 m0, s61
	s_nop 0
	global_load_lds_dwordx4 v[140:141], off
	v_lshl_add_u64 v[140:141], v[248:249], 0, s[26:27]
	s_mov_b32 m0, s62
	s_nop 0
	global_load_lds_dwordx4 v[140:141], off
	s_waitcnt vmcnt(7)
	s_waitcnt lgkmcnt(0)
	s_barrier
	s_setprio 1
	s_waitcnt lgkmcnt(0)
	v_mfma_f32_16x16x32_bf16 v[62:65], v[146:149], v[178:181], v[62:65]
	v_mfma_f32_16x16x32_bf16 v[54:57], v[154:157], v[178:181], v[54:57]
	v_mfma_f32_16x16x32_bf16 v[46:49], v[146:149], v[224:227], v[46:49]
	v_mfma_f32_16x16x32_bf16 v[38:41], v[154:157], v[224:227], v[38:41]
	v_mfma_f32_16x16x32_bf16 v[30:33], v[146:149], v[232:235], v[30:33]
	v_mfma_f32_16x16x32_bf16 v[22:25], v[154:157], v[232:235], v[22:25]
	v_mfma_f32_16x16x32_bf16 v[14:17], v[146:149], v[240:243], v[14:17]
	v_mfma_f32_16x16x32_bf16 v[6:9], v[154:157], v[240:243], v[6:9]
	v_mfma_f32_16x16x32_bf16 v[62:65], v[150:153], v[182:185], v[62:65]
	v_mfma_f32_16x16x32_bf16 v[54:57], v[158:161], v[182:185], v[54:57]
	v_mfma_f32_16x16x32_bf16 v[46:49], v[150:153], v[228:231], v[46:49]
	v_mfma_f32_16x16x32_bf16 v[38:41], v[158:161], v[228:231], v[38:41]
	v_mfma_f32_16x16x32_bf16 v[30:33], v[150:153], v[236:239], v[30:33]
	v_mfma_f32_16x16x32_bf16 v[22:25], v[158:161], v[236:239], v[22:25]
	v_mfma_f32_16x16x32_bf16 v[14:17], v[150:153], v[244:247], v[14:17]
	v_mfma_f32_16x16x32_bf16 v[6:9], v[158:161], v[244:247], v[6:9]
	s_setprio 0
	s_setprio 1
	v_mfma_f32_16x16x32_bf16 v[58:61], v[162:165], v[178:181], v[58:61]
	v_mfma_f32_16x16x32_bf16 v[50:53], v[170:173], v[178:181], v[50:53]
	v_mfma_f32_16x16x32_bf16 v[42:45], v[162:165], v[224:227], v[42:45]
	v_mfma_f32_16x16x32_bf16 v[34:37], v[170:173], v[224:227], v[34:37]
	v_mfma_f32_16x16x32_bf16 v[26:29], v[162:165], v[232:235], v[26:29]
	v_mfma_f32_16x16x32_bf16 v[18:21], v[170:173], v[232:235], v[18:21]
	v_mfma_f32_16x16x32_bf16 v[10:13], v[162:165], v[240:243], v[10:13]
	v_mfma_f32_16x16x32_bf16 v[2:5], v[170:173], v[240:243], v[2:5]
	v_mfma_f32_16x16x32_bf16 v[58:61], v[166:169], v[182:185], v[58:61]
	v_mfma_f32_16x16x32_bf16 v[50:53], v[174:177], v[182:185], v[50:53]
	v_mfma_f32_16x16x32_bf16 v[42:45], v[166:169], v[228:231], v[42:45]
	v_mfma_f32_16x16x32_bf16 v[34:37], v[174:177], v[228:231], v[34:37]
	v_mfma_f32_16x16x32_bf16 v[26:29], v[166:169], v[236:239], v[26:29]
	v_mfma_f32_16x16x32_bf16 v[18:21], v[174:177], v[236:239], v[18:21]
	v_mfma_f32_16x16x32_bf16 v[10:13], v[166:169], v[244:247], v[10:13]
	v_mfma_f32_16x16x32_bf16 v[2:5], v[174:177], v[244:247], v[2:5]
	s_setprio 0
	s_barrier
	s_add_i32 s72, s72, 2
	s_add_u32 s50, s50, 0x100
	s_addc_u32 s51, s51, 0
	s_add_u32 s68, s68, 0x100
	s_addc_u32 s69, s69, 0
	s_cmp_gt_u32 s72, 13
	s_cbranch_scc0 .LBB0_120
	s_and_b64 vcc, exec, s[24:25]
	s_mov_b64 s[68:69], s[36:37]
	s_cbranch_vccz .LBB0_123
	s_barrier
